# GLA chain loop: global ops with counted vmcnt waits instead of a full drain per step
# baseline (speedup 1.0000x reference)
.LBB0_491:
	s_or_b64 exec, exec, s[40:41]
	s_lshl_b32 s71, s11, 8
	s_lshl_b32 s0, s42, 25
	v_readlane_b32 s1, v254, 61
	s_add_u32 s68, s1, s0
	v_readlane_b32 s0, v254, 63
	s_addc_u32 s69, s0, 0
	s_add_i32 s71, s71, s76
	s_add_i32 s78, s43, -4
	s_mov_b32 s79, 3
	s_waitcnt vmcnt(0)
	s_branch .LBB0_494

.LBB0_493:
	v_lshlrev_b32_e32 v0, 3, v215
	v_mul_lo_u32 v15, v14, s64
	v_add3_u32 v15, 0, v0, v15
	v_cvt_pk_bf16_f32 v96, v16, v17
	v_cvt_pk_bf16_f32 v97, v18, v19
	v_cvt_pk_bf16_f32 v98, v20, v21
	v_cvt_pk_bf16_f32 v99, v22, v23
	ds_read2_b64 v[80:83], v15 offset1:2
	ds_read2_b64 v[238:241], v15 offset0:4 offset1:6
	v_add_u32_e32 v196, 0x2000, v15
	s_waitcnt lgkmcnt(0)
	v_mfma_f32_32x32x16_bf16 v[80:95], v[96:99], v[80:83], 0
	ds_read2_b64 v[100:103], v196 offset0:64 offset1:66
	v_cvt_pk_bf16_f32 v242, v24, v25
	v_cvt_pk_bf16_f32 v243, v26, v27
	v_cvt_pk_bf16_f32 v244, v28, v29
	v_cvt_pk_bf16_f32 v245, v30, v31
	v_cvt_pk_bf16_f32 v112, v32, v33
	v_cvt_pk_bf16_f32 v113, v34, v35
	v_cvt_pk_bf16_f32 v114, v36, v37
	v_cvt_pk_bf16_f32 v115, v38, v39
	s_waitcnt lgkmcnt(0)
	v_mfma_f32_32x32x16_bf16 v[96:111], v[96:99], v[100:103], 0
	ds_read2_b64 v[116:119], v15 offset0:8 offset1:10
	v_cvt_pk_bf16_f32 v246, v40, v41
	v_cvt_pk_bf16_f32 v247, v42, v43
	v_cvt_pk_bf16_f32 v248, v44, v45
	v_cvt_pk_bf16_f32 v249, v46, v47
	s_add_i32 s4, s79, -2
	s_add_i32 s5, s78, 2
	v_mfma_f32_32x32x16_bf16 v[80:95], v[242:245], v[238:241], v[80:95]
	ds_read2_b64 v[238:241], v196 offset0:68 offset1:70
	s_and_b64 s[0:1], s[34:35], exec
	s_cselect_b32 s0, s4, s5
	s_lshl_b32 s0, s0, 6
	s_add_i32 s38, s0, s44
	s_ashr_i32 s39, s38, 31
	s_add_i32 s78, s78, -2
	s_waitcnt lgkmcnt(0)
	v_mfma_f32_32x32x16_bf16 v[128:143], v[112:115], v[116:119], 0
	ds_read2_b64 v[116:119], v196 offset0:72 offset1:74
	s_add_i32 s79, s79, 2
	s_cmp_ge_u32 s80, s43
	v_mfma_f32_32x32x16_bf16 v[96:111], v[242:245], v[238:241], v[96:111]
	ds_read2_b64 v[238:241], v15 offset0:12 offset1:14
	v_cvt_pk_bf16_f32 v242, v64, v65
	v_cvt_pk_bf16_f32 v243, v66, v67
	v_cvt_pk_bf16_f32 v244, v68, v69
	v_cvt_pk_bf16_f32 v245, v70, v71
	s_waitcnt lgkmcnt(0)
	v_mfma_f32_32x32x16_bf16 v[112:127], v[112:115], v[116:119], 0
	v_mfma_f32_32x32x16_bf16 v[128:143], v[246:249], v[238:241], v[128:143]
	ds_read2_b64 v[238:241], v196 offset0:76 offset1:78
	s_waitcnt lgkmcnt(0)
	v_mfma_f32_32x32x16_bf16 v[112:127], v[246:249], v[238:241], v[112:127]
	v_cvt_pk_bf16_f32 v238, v48, v49
	v_cvt_pk_bf16_f32 v239, v50, v51
	v_cvt_pk_bf16_f32 v240, v52, v53
	v_cvt_pk_bf16_f32 v241, v54, v55
	ds_read2_b64 v[246:249], v15 offset0:16 offset1:18
	s_waitcnt lgkmcnt(0)
	v_mfma_f32_32x32x16_bf16 v[80:95], v[238:241], v[246:249], v[80:95]
	ds_read2_b64 v[246:249], v196 offset0:80 offset1:82
	s_waitcnt lgkmcnt(0)
	v_mfma_f32_32x32x16_bf16 v[96:111], v[238:241], v[246:249], v[96:111]
	ds_read2_b64 v[238:241], v15 offset0:24 offset1:26
	ds_read2_b64 v[246:249], v15 offset0:20 offset1:22
	s_waitcnt lgkmcnt(0)
	v_mfma_f32_32x32x16_bf16 v[128:143], v[242:245], v[238:241], v[128:143]
	ds_read2_b64 v[238:241], v196 offset0:88 offset1:90
	s_waitcnt lgkmcnt(0)
	v_mfma_f32_32x32x16_bf16 v[112:127], v[242:245], v[238:241], v[112:127]
	v_cvt_pk_bf16_f32 v238, v56, v57
	v_cvt_pk_bf16_f32 v239, v58, v59
	v_cvt_pk_bf16_f32 v240, v60, v61
	v_cvt_pk_bf16_f32 v241, v62, v63
	v_cvt_pk_bf16_f32 v242, v72, v73
	v_cvt_pk_bf16_f32 v243, v74, v75
	v_cvt_pk_bf16_f32 v244, v76, v77
	v_mfma_f32_32x32x16_bf16 v[80:95], v[238:241], v[246:249], v[80:95]
	ds_read2_b64 v[246:249], v196 offset0:84 offset1:86
	v_cvt_pk_bf16_f32 v245, v78, v79
	s_waitcnt lgkmcnt(0)
	v_mfma_f32_32x32x16_bf16 v[96:111], v[238:241], v[246:249], v[96:111]
	ds_read2_b64 v[238:241], v15 offset0:28 offset1:30
	v_ashrrev_i32_e32 v15, 31, v14
	s_waitcnt lgkmcnt(0)
	v_mfma_f32_32x32x16_bf16 v[128:143], v[242:245], v[238:241], v[128:143]
	ds_read2_b64 v[238:241], v196 offset0:92 offset1:94
	v_lshl_add_u32 v196, v215, 2, s71
	v_ashrrev_i32_e32 v197, 31, v196
	v_lshlrev_b64 v[196:197], 15, v[196:197]
	v_lshl_add_u64 v[196:197], s[68:69], 0, v[196:197]
	v_lshl_add_u64 v[196:197], s[38:39], 1, v[196:197]
	v_lshl_add_u64 v[196:197], v[14:15], 1, v[196:197]
	s_waitcnt lgkmcnt(0)
	v_mfma_f32_32x32x16_bf16 v[112:127], v[242:245], v[238:241], v[112:127]
	s_nop 2
	v_add_f32_e32 v15, v80, v128
	v_bfe_u32 v80, v15, 16, 1
	v_add3_u32 v15, v15, v80, s55
	global_store_short_d16_hi v[196:197], v15, off
	s_nop 4
	v_add_f32_e32 v15, v96, v112
	v_bfe_u32 v80, v15, 16, 1
	v_add3_u32 v15, v15, v80, s55
	global_store_short_d16_hi v[196:197], v15, off offset:64
	v_add_f32_e32 v15, v81, v129
	v_bfe_u32 v80, v15, 16, 1
	v_add3_u32 v15, v15, v80, s55
	v_add_co_u32_e32 v80, vcc, s47, v196
	s_nop 1
	v_addc_co_u32_e32 v81, vcc, 0, v197, vcc
	global_store_short_d16_hi v[80:81], v15, off
	v_add_f32_e32 v15, v97, v113
	v_bfe_u32 v96, v15, 16, 1
	v_add3_u32 v15, v15, v96, s55
	global_store_short_d16_hi v[80:81], v15, off offset:64
	v_add_f32_e32 v15, v82, v130
	v_bfe_u32 v80, v15, 16, 1
	v_add3_u32 v15, v15, v80, s55
	v_add_co_u32_e32 v80, vcc, s33, v196
	s_nop 1
	v_addc_co_u32_e32 v81, vcc, 0, v197, vcc
	global_store_short_d16_hi v[80:81], v15, off
	v_add_f32_e32 v15, v98, v114
	v_bfe_u32 v82, v15, 16, 1
	v_add3_u32 v15, v15, v82, s55
	global_store_short_d16_hi v[80:81], v15, off offset:64
	v_add_f32_e32 v15, v83, v131
	v_bfe_u32 v80, v15, 16, 1
	v_add3_u32 v15, v15, v80, s55
	v_add_co_u32_e32 v80, vcc, s46, v196
	s_nop 1
	v_addc_co_u32_e32 v81, vcc, 0, v197, vcc
	global_store_short_d16_hi v[80:81], v15, off
	v_add_f32_e32 v15, v99, v115
	v_bfe_u32 v82, v15, 16, 1
	v_add3_u32 v15, v15, v82, s55
	global_store_short_d16_hi v[80:81], v15, off offset:64
	v_add_f32_e32 v15, v84, v132
	v_bfe_u32 v80, v15, 16, 1
	v_add3_u32 v15, v15, v80, s55
	v_add_co_u32_e32 v80, vcc, s82, v196
	s_nop 1
	v_addc_co_u32_e32 v81, vcc, 0, v197, vcc
	global_store_short_d16_hi v[80:81], v15, off
	v_add_f32_e32 v15, v100, v116
	v_bfe_u32 v82, v15, 16, 1
	v_add3_u32 v15, v15, v82, s55
	global_store_short_d16_hi v[80:81], v15, off offset:64
	v_add_f32_e32 v15, v85, v133
	v_bfe_u32 v80, v15, 16, 1
	v_add3_u32 v15, v15, v80, s55
	v_add_co_u32_e32 v80, vcc, s83, v196
	s_nop 1
	v_addc_co_u32_e32 v81, vcc, 0, v197, vcc
	global_store_short_d16_hi v[80:81], v15, off
	v_add_f32_e32 v15, v101, v117
	v_bfe_u32 v82, v15, 16, 1
	v_add3_u32 v15, v15, v82, s55
	global_store_short_d16_hi v[80:81], v15, off offset:64
	v_add_f32_e32 v15, v86, v134
	v_bfe_u32 v80, v15, 16, 1
	v_add3_u32 v15, v15, v80, s55
	v_add_co_u32_e32 v80, vcc, s54, v196
	s_nop 1
	v_addc_co_u32_e32 v81, vcc, 0, v197, vcc
	global_store_short_d16_hi v[80:81], v15, off
	v_add_f32_e32 v15, v102, v118
	v_bfe_u32 v82, v15, 16, 1
	v_add3_u32 v15, v15, v82, s55
	global_store_short_d16_hi v[80:81], v15, off offset:64
	v_add_f32_e32 v15, v87, v135
	v_bfe_u32 v80, v15, 16, 1
	v_add3_u32 v15, v15, v80, s55
	v_add_co_u32_e32 v80, vcc, s88, v196
	s_nop 1
	v_addc_co_u32_e32 v81, vcc, 0, v197, vcc
	global_store_short_d16_hi v[80:81], v15, off
	v_add_f32_e32 v15, v103, v119
	v_bfe_u32 v82, v15, 16, 1
	v_add3_u32 v15, v15, v82, s55
	global_store_short_d16_hi v[80:81], v15, off offset:64
	v_add_f32_e32 v15, v88, v136
	v_bfe_u32 v80, v15, 16, 1
	v_add3_u32 v15, v15, v80, s55
	v_add_co_u32_e32 v80, vcc, s48, v196
	s_nop 1
	v_addc_co_u32_e32 v81, vcc, 0, v197, vcc
	global_store_short_d16_hi v[80:81], v15, off
	v_add_f32_e32 v15, v104, v120
	v_bfe_u32 v82, v15, 16, 1
	v_add3_u32 v15, v15, v82, s55
	global_store_short_d16_hi v[80:81], v15, off offset:64
	v_add_f32_e32 v15, v89, v137
	v_bfe_u32 v80, v15, 16, 1
	v_add3_u32 v15, v15, v80, s55
	v_add_co_u32_e32 v80, vcc, s51, v196
	s_nop 1
	v_addc_co_u32_e32 v81, vcc, 0, v197, vcc
	global_store_short_d16_hi v[80:81], v15, off
	v_add_f32_e32 v15, v105, v121
	v_bfe_u32 v82, v15, 16, 1
	v_add3_u32 v15, v15, v82, s55
	global_store_short_d16_hi v[80:81], v15, off offset:64
	v_add_f32_e32 v15, v90, v138
	v_bfe_u32 v80, v15, 16, 1
	v_add3_u32 v15, v15, v80, s55
	v_add_co_u32_e32 v80, vcc, s52, v196
	s_nop 1
	v_addc_co_u32_e32 v81, vcc, 0, v197, vcc
	global_store_short_d16_hi v[80:81], v15, off
	v_add_f32_e32 v15, v106, v122
	v_bfe_u32 v82, v15, 16, 1
	v_add3_u32 v15, v15, v82, s55
	global_store_short_d16_hi v[80:81], v15, off offset:64
	v_add_f32_e32 v15, v91, v139
	v_bfe_u32 v80, v15, 16, 1
	v_add3_u32 v15, v15, v80, s55
	v_add_co_u32_e32 v80, vcc, s90, v196
	s_nop 1
	v_addc_co_u32_e32 v81, vcc, 0, v197, vcc
	global_store_short_d16_hi v[80:81], v15, off
	v_add_f32_e32 v15, v107, v123
	v_bfe_u32 v82, v15, 16, 1
	v_add3_u32 v15, v15, v82, s55
	global_store_short_d16_hi v[80:81], v15, off offset:64
	v_add_f32_e32 v15, v92, v140
	v_bfe_u32 v80, v15, 16, 1
	v_add3_u32 v15, v15, v80, s55
	v_add_co_u32_e32 v80, vcc, s91, v196
	s_nop 1
	v_addc_co_u32_e32 v81, vcc, 0, v197, vcc
	global_store_short_d16_hi v[80:81], v15, off
	v_add_f32_e32 v15, v108, v124
	v_bfe_u32 v82, v15, 16, 1
	v_add3_u32 v15, v15, v82, s55
	global_store_short_d16_hi v[80:81], v15, off offset:64
	v_add_f32_e32 v15, v93, v141
	v_bfe_u32 v80, v15, 16, 1
	v_add3_u32 v15, v15, v80, s55
	v_add_co_u32_e32 v80, vcc, s84, v196
	s_nop 1
	v_addc_co_u32_e32 v81, vcc, 0, v197, vcc
	global_store_short_d16_hi v[80:81], v15, off
	v_add_f32_e32 v15, v109, v125
	v_bfe_u32 v82, v15, 16, 1
	v_add3_u32 v15, v15, v82, s55
	global_store_short_d16_hi v[80:81], v15, off offset:64
	v_add_f32_e32 v15, v94, v142
	v_bfe_u32 v80, v15, 16, 1
	v_add3_u32 v15, v15, v80, s55
	v_add_co_u32_e32 v80, vcc, s65, v196
	s_nop 1
	v_addc_co_u32_e32 v81, vcc, 0, v197, vcc
	global_store_short_d16_hi v[80:81], v15, off
	v_add_f32_e32 v15, v110, v126
	v_bfe_u32 v82, v15, 16, 1
	v_add3_u32 v15, v15, v82, s55
	global_store_short_d16_hi v[80:81], v15, off offset:64
	v_add_f32_e32 v15, v95, v143
	v_bfe_u32 v80, v15, 16, 1
	v_add3_u32 v15, v15, v80, s55
	v_add_co_u32_e32 v80, vcc, s66, v196
	s_nop 1
	v_addc_co_u32_e32 v81, vcc, 0, v197, vcc
	global_store_short_d16_hi v[80:81], v15, off
	v_add_f32_e32 v15, v111, v127
	v_bfe_u32 v82, v15, 16, 1
	v_add3_u32 v15, v15, v82, s55
	global_store_short_d16_hi v[80:81], v15, off offset:64
	v_lshl_add_u32 v15, v215, 4, 0
	v_add_u32_e32 v15, 0x17400, v15
	ds_read_b128 v[80:83], v15
	ds_read_b128 v[84:87], v15 offset:32
	ds_read_b128 v[88:91], v15 offset:64
	ds_read_b128 v[92:95], v15 offset:96
	s_waitcnt lgkmcnt(0)
	v_pk_mul_f32 v[18:19], v[18:19], v[82:83]
	v_pk_mul_f32 v[22:23], v[22:23], v[86:87]
	v_pk_mul_f32 v[26:27], v[26:27], v[90:91]
	v_pk_mul_f32 v[30:31], v[30:31], v[94:95]
	v_pk_mul_f32 v[28:29], v[28:29], v[92:93]
	v_pk_mul_f32 v[24:25], v[24:25], v[88:89]
	v_pk_mul_f32 v[20:21], v[20:21], v[84:85]
	v_pk_mul_f32 v[16:17], v[16:17], v[80:81]
	ds_read_b128 v[80:83], v15 offset:128
	ds_read_b128 v[84:87], v15 offset:160
	ds_read_b128 v[88:91], v15 offset:192
	ds_read_b128 v[92:95], v15 offset:224
	s_waitcnt lgkmcnt(0)
	v_pk_mul_f32 v[34:35], v[34:35], v[82:83]
	v_pk_mul_f32 v[38:39], v[38:39], v[86:87]
	v_pk_mul_f32 v[42:43], v[42:43], v[90:91]
	v_pk_mul_f32 v[46:47], v[46:47], v[94:95]
	v_pk_mul_f32 v[44:45], v[44:45], v[92:93]
	v_pk_mul_f32 v[40:41], v[40:41], v[88:89]
	v_pk_mul_f32 v[36:37], v[36:37], v[84:85]
	v_pk_mul_f32 v[32:33], v[32:33], v[80:81]
	ds_read_b128 v[80:83], v15 offset:256
	ds_read_b128 v[84:87], v15 offset:288
	ds_read_b128 v[88:91], v15 offset:320
	ds_read_b128 v[92:95], v15 offset:352
	s_waitcnt lgkmcnt(0)
	v_pk_mul_f32 v[50:51], v[50:51], v[82:83]
	v_pk_mul_f32 v[54:55], v[54:55], v[86:87]
	v_pk_mul_f32 v[58:59], v[58:59], v[90:91]
	v_pk_mul_f32 v[62:63], v[62:63], v[94:95]
	v_pk_mul_f32 v[60:61], v[60:61], v[92:93]
	v_pk_mul_f32 v[56:57], v[56:57], v[88:89]
	v_pk_mul_f32 v[52:53], v[52:53], v[84:85]
	v_pk_mul_f32 v[48:49], v[48:49], v[80:81]
	ds_read_b128 v[80:83], v15 offset:384
	ds_read_b128 v[84:87], v15 offset:416
	ds_read_b128 v[88:91], v15 offset:448
	ds_read_b128 v[92:95], v15 offset:480
	v_add_u32_e32 v15, s76, v14
	s_waitcnt lgkmcnt(0)
	v_pk_mul_f32 v[64:65], v[64:65], v[80:81]
	v_mad_u64_u32 v[80:81], s[0:1], v15, s53, v[0:1]
	v_mul_lo_u32 v14, v14, s63
	v_lshl_add_u32 v15, v80, 1, 0
	v_add_u32_e32 v80, v0, v14
	v_lshl_add_u32 v80, v80, 1, 0
	v_add_u32_e32 v80, 0x8800, v80
	v_pk_mul_f32 v[74:75], v[74:75], v[90:91]
	v_pk_mul_f32 v[70:71], v[70:71], v[86:87]
	v_pk_mul_f32 v[66:67], v[66:67], v[82:83]
	v_pk_mul_f32 v[72:73], v[72:73], v[88:89]
	v_pk_mul_f32 v[68:69], v[68:69], v[84:85]
	ds_read2_b64 v[80:83], v80 offset1:1
	ds_read_b128 v[84:87], v15 offset:52224
	ds_read_b128 v[88:91], v15 offset:52256
	v_pk_mul_f32 v[76:77], v[76:77], v[92:93]
	v_add_u32_e32 v92, 0x880, v14
	s_waitcnt lgkmcnt(0)
	v_mfma_f32_32x32x16_bf16 v[16:31], v[80:83], v[84:87], v[16:31]
	v_add_u32_e32 v80, v92, v0
	v_lshl_add_u32 v80, v80, 1, 0
	v_add_u32_e32 v80, 0x8800, v80
	ds_read2_b64 v[80:83], v80 offset1:1
	v_add_u32_e32 v93, 0x1100, v14
	v_pk_mul_f32 v[78:79], v[78:79], v[94:95]
	v_add_u32_e32 v94, 0x1980, v14
	s_waitcnt lgkmcnt(0)
	v_mfma_f32_32x32x16_bf16 v[32:47], v[80:83], v[84:87], v[32:47]
	v_add_u32_e32 v80, v93, v0
	v_lshl_add_u32 v80, v80, 1, 0
	v_add_u32_e32 v80, 0x8800, v80
	ds_read2_b64 v[80:83], v80 offset1:1
	s_waitcnt lgkmcnt(0)
	v_mfma_f32_32x32x16_bf16 v[48:63], v[80:83], v[84:87], v[48:63]
	v_add_u32_e32 v80, v94, v0
	v_lshl_add_u32 v80, v80, 1, 0
	v_add_u32_e32 v80, 0x8800, v80
	ds_read2_b64 v[80:83], v80 offset1:1
	s_waitcnt lgkmcnt(0)
	v_mfma_f32_32x32x16_bf16 v[64:79], v[80:83], v[84:87], v[64:79]
	v_add_u32_e32 v84, 16, v0
	v_add_u32_e32 v80, v84, v14
	v_lshl_add_u32 v80, v80, 1, 0
	v_add_u32_e32 v80, 0x8800, v80
	ds_read2_b64 v[80:83], v80 offset1:1
	s_waitcnt lgkmcnt(0)
	v_mfma_f32_32x32x16_bf16 v[16:31], v[80:83], v[88:91], v[16:31]
	v_add_u32_e32 v80, v84, v92
	v_lshl_add_u32 v80, v80, 1, 0
	v_add_u32_e32 v80, 0x8800, v80
	ds_read2_b64 v[80:83], v80 offset1:1
	s_waitcnt lgkmcnt(0)
	v_mfma_f32_32x32x16_bf16 v[32:47], v[80:83], v[88:91], v[32:47]
	v_add_u32_e32 v80, v84, v93
	v_lshl_add_u32 v80, v80, 1, 0
	v_add_u32_e32 v80, 0x8800, v80
	ds_read2_b64 v[80:83], v80 offset1:1
	s_waitcnt lgkmcnt(0)
	v_mfma_f32_32x32x16_bf16 v[48:63], v[80:83], v[88:91], v[48:63]
	v_add_u32_e32 v80, v84, v94
	v_lshl_add_u32 v80, v80, 1, 0
	v_add_u32_e32 v80, 0x8800, v80
	ds_read2_b64 v[80:83], v80 offset1:1
	s_waitcnt lgkmcnt(0)
	v_mfma_f32_32x32x16_bf16 v[64:79], v[80:83], v[88:91], v[64:79]
	v_add_u32_e32 v88, 32, v0
	v_add_u32_e32 v84, v88, v14
	v_lshl_add_u32 v84, v84, 1, 0
	v_add_u32_e32 v84, 0x8800, v84
	ds_read_b128 v[80:83], v15 offset:52288
	ds_read2_b64 v[84:87], v84 offset1:1
	v_add_u32_e32 v0, 48, v0
	s_waitcnt lgkmcnt(0)
	v_mfma_f32_32x32x16_bf16 v[16:31], v[84:87], v[80:83], v[16:31]
	v_add_u32_e32 v84, v88, v92
	v_lshl_add_u32 v84, v84, 1, 0
	v_add_u32_e32 v84, 0x8800, v84
	ds_read2_b64 v[84:87], v84 offset1:1
	v_add_u32_e32 v14, v0, v14
	v_lshl_add_u32 v14, v14, 1, 0
	v_add_u32_e32 v14, 0x8800, v14
	s_waitcnt lgkmcnt(0)
	v_mfma_f32_32x32x16_bf16 v[32:47], v[84:87], v[80:83], v[32:47]
	v_add_u32_e32 v84, v88, v93
	v_lshl_add_u32 v84, v84, 1, 0
	v_add_u32_e32 v84, 0x8800, v84
	ds_read2_b64 v[84:87], v84 offset1:1
	s_waitcnt lgkmcnt(0)
	v_mfma_f32_32x32x16_bf16 v[48:63], v[84:87], v[80:83], v[48:63]
	v_add_u32_e32 v84, v88, v94
	v_lshl_add_u32 v84, v84, 1, 0
	v_add_u32_e32 v84, 0x8800, v84
	ds_read2_b64 v[84:87], v84 offset1:1
	s_waitcnt lgkmcnt(0)
	v_mfma_f32_32x32x16_bf16 v[64:79], v[84:87], v[80:83], v[64:79]
	ds_read_b128 v[80:83], v15 offset:52320
	ds_read2_b64 v[84:87], v14 offset1:1
	v_add_u32_e32 v14, v0, v92
	v_lshl_add_u32 v14, v14, 1, 0
	v_add_u32_e32 v14, 0x8800, v14
	s_waitcnt lgkmcnt(0)
	v_mfma_f32_32x32x16_bf16 v[16:31], v[84:87], v[80:83], v[16:31]
	ds_read2_b64 v[84:87], v14 offset1:1
	v_add_u32_e32 v14, v0, v93
	v_lshl_add_u32 v14, v14, 1, 0
	v_add_u32_e32 v14, 0x8800, v14
	v_add_u32_e32 v0, v0, v94
	v_lshl_add_u32 v0, v0, 1, 0
	v_add_u32_e32 v0, 0x8800, v0
	s_waitcnt lgkmcnt(0)
	v_mfma_f32_32x32x16_bf16 v[32:47], v[84:87], v[80:83], v[32:47]
	ds_read2_b64 v[84:87], v14 offset1:1
	s_waitcnt lgkmcnt(0)
	v_mfma_f32_32x32x16_bf16 v[48:63], v[84:87], v[80:83], v[48:63]
	ds_read2_b64 v[84:87], v0 offset1:1
	s_waitcnt lgkmcnt(0)
	v_mfma_f32_32x32x16_bf16 v[64:79], v[84:87], v[80:83], v[64:79]
	s_cbranch_scc1 .LBB0_505
.LBB0_494:
	v_mov_b32_e32 v215, v209
	v_mov_b32_e32 v14, v208
	v_mov_b32_e32 v0, v236
	s_waitcnt lgkmcnt(0)
	v_lshlrev_b32_e32 v82, 3, v0
	v_ashrrev_i32_e32 v15, 4, v0
	v_and_b32_e32 v80, 0x78, v82
	v_mad_u64_u32 v[80:81], s[0:1], v15, s31, v[80:81]
	v_lshl_add_u32 v15, v80, 1, 0
	s_barrier
	s_waitcnt vmcnt(63)
	ds_write_b128 v15, v[2:5]
	ds_write_b128 v15, v[6:9] offset:8704
	v_ashrrev_i32_e32 v15, 3, v0
	v_and_b32_e32 v80, 56, v82
	v_mad_u64_u32 v[82:83], s[0:1], v15, s63, v[80:81]
	v_lshl_add_u32 v81, v82, 1, 0
	v_lshl_add_u32 v15, v15, 2, v82
	v_add_u32_e32 v83, 0x8800, v81
	v_lshl_add_u32 v15, v15, 1, 0
	v_add_u32_e32 v81, 0xaa00, v81
	ds_write2_b64 v83, v[10:11], v[12:13] offset1:1
	ds_write2_b64 v81, v[144:145], v[146:147] offset1:1
	ds_write_b128 v15, v[148:151] offset:52224
	v_add_u32_e32 v15, 0x200, v0
	v_lshrrev_b32_e32 v15, 3, v15
	v_mad_u64_u32 v[82:83], s[0:1], v15, s53, v[80:81]
	v_lshl_add_u32 v15, v82, 1, 0
	ds_write_b128 v15, v[152:155] offset:52224
	v_add_u32_e32 v15, 0x400, v0
	v_lshrrev_b32_e32 v15, 3, v15
	v_mad_u64_u32 v[82:83], s[0:1], v15, s53, v[80:81]
	v_lshl_add_u32 v15, v82, 1, 0
	ds_write_b128 v15, v[156:159] offset:52224
	v_add_u32_e32 v15, 0x600, v0
	v_lshrrev_b32_e32 v15, 3, v15
	v_mad_u64_u32 v[80:81], s[0:1], v15, s53, v[80:81]
	v_lshl_add_u32 v15, v80, 1, 0
	v_cmp_gt_i32_e32 vcc, s60, v0
	ds_write_b128 v15, v[160:163] offset:52224
	s_and_saveexec_b64 s[38:39], vcc
	v_lshl_add_u32 v0, v0, 2, 0
	v_add_u32_e32 v0, 0x17400, v0
	ds_write_b32 v0, v214
	s_or_b64 exec, exec, s[38:39]
	s_add_i32 s80, s79, -1
	s_cmp_ge_u32 s80, s43
	s_waitcnt lgkmcnt(0)
	s_barrier
	s_cbranch_scc1 .LBB0_500
	s_add_i32 s4, s78, 1
	s_and_b64 s[0:1], s[34:35], exec
	s_cselect_b32 s0, s80, s4
	s_lshl_b32 s0, s0, 6
	s_add_i32 s0, s0, s44
	s_ashr_i32 s1, s0, 4
	s_or_b32 s1, s1, s11
	s_lshl_b32 s1, s1, 1
	s_or_b32 s38, s1, s42
	s_ashr_i32 s39, s38, 31
	s_lshl_b64 s[4:5], s[38:39], 14
	s_add_u32 s6, s92, s4
	s_addc_u32 s7, s93, s5
	s_add_u32 s4, s73, s4
	v_mov_b32_e32 v80, v236
	s_addc_u32 s5, s74, s5
	s_ashr_i32 s1, s0, 31
	v_lshlrev_b32_e32 v0, 3, v80
	v_add_u32_e32 v4, 0x1000, v0
	v_mov_b32_e32 v5, v1
	s_lshl_b64 s[0:1], s[0:1], 1
	v_lshlrev_b64 v[10:11], 1, v[0:1]
	v_lshlrev_b64 v[12:13], 1, v[4:5]
	s_add_u32 s0, s45, s0
	v_lshlrev_b32_e32 v15, 11, v80
	v_and_b32_e32 v0, 56, v0
	v_lshl_add_u64 v[2:3], s[6:7], 0, v[10:11]
	v_lshl_add_u64 v[6:7], s[6:7], 0, v[12:13]
	v_lshl_add_u64 v[10:11], s[4:5], 0, v[10:11]
	v_lshl_add_u64 v[82:83], s[4:5], 0, v[12:13]
	s_addc_u32 s1, s70, s1
	v_and_or_b32 v0, v15, s62, v0
	global_load_dwordx4 v[2:5], v[2:3], off
	s_nop 0
	global_load_dwordx4 v[6:9], v[6:7], off
	s_nop 0
	global_load_dwordx4 v[10:13], v[10:11], off
	s_nop 0
	global_load_dwordx4 v[144:147], v[82:83], off
	v_lshl_add_u64 v[82:83], v[0:1], 1, s[0:1]
	v_add_u32_e32 v84, 0x100000, v0
	v_mov_b32_e32 v85, v1
	v_lshl_add_u64 v[84:85], v[84:85], 1, s[0:1]
	global_load_dwordx4 v[148:151], v[82:83], off
	global_load_dwordx4 v[152:155], v[84:85], off
	v_add_u32_e32 v82, 0x200000, v0
	v_mov_b32_e32 v83, v1
	v_lshl_add_u64 v[82:83], v[82:83], 1, s[0:1]
	v_add_u32_e32 v0, 0x300000, v0
	v_lshl_add_u64 v[84:85], v[0:1], 1, s[0:1]
	global_load_dwordx4 v[156:159], v[82:83], off
	global_load_dwordx4 v[160:163], v[84:85], off
	v_cmp_gt_i32_e32 vcc, s60, v80
	s_and_saveexec_b64 s[40:41], vcc
	s_cbranch_execz .LBB0_499
	s_lshl_b64 s[0:1], s[38:39], 9
	s_add_u32 s0, s75, s0
	s_addc_u32 s1, s86, s1
	v_mov_b32_e32 v81, v1
	v_lshl_add_u64 v[80:81], v[80:81], 2, s[0:1]
	global_load_dword v214, v[80:81], off

.LBB0_500:
	v_lshlrev_b32_e32 v0, 3, v215
	v_mul_lo_u32 v15, v14, s64
	v_add3_u32 v15, 0, v0, v15
	v_cvt_pk_bf16_f32 v96, v16, v17
	v_cvt_pk_bf16_f32 v97, v18, v19
	v_cvt_pk_bf16_f32 v98, v20, v21
	v_cvt_pk_bf16_f32 v99, v22, v23
	ds_read2_b64 v[80:83], v15 offset1:2
	ds_read2_b64 v[238:241], v15 offset0:4 offset1:6
	v_add_u32_e32 v196, 0x2000, v15
	s_waitcnt lgkmcnt(0)
	v_mfma_f32_32x32x16_bf16 v[80:95], v[96:99], v[80:83], 0
	ds_read2_b64 v[100:103], v196 offset0:64 offset1:66
	v_cvt_pk_bf16_f32 v242, v24, v25
	v_cvt_pk_bf16_f32 v243, v26, v27
	v_cvt_pk_bf16_f32 v244, v28, v29
	v_cvt_pk_bf16_f32 v245, v30, v31
	v_cvt_pk_bf16_f32 v112, v32, v33
	v_cvt_pk_bf16_f32 v113, v34, v35
	v_cvt_pk_bf16_f32 v114, v36, v37
	v_cvt_pk_bf16_f32 v115, v38, v39
	s_waitcnt lgkmcnt(0)
	v_mfma_f32_32x32x16_bf16 v[96:111], v[96:99], v[100:103], 0
	ds_read2_b64 v[116:119], v15 offset0:8 offset1:10
	v_cvt_pk_bf16_f32 v246, v40, v41
	v_cvt_pk_bf16_f32 v247, v42, v43
	v_cvt_pk_bf16_f32 v248, v44, v45
	v_cvt_pk_bf16_f32 v249, v46, v47
	s_add_i32 s4, s79, -3
	s_add_i32 s5, s78, 3
	v_mfma_f32_32x32x16_bf16 v[80:95], v[242:245], v[238:241], v[80:95]
	ds_read2_b64 v[238:241], v196 offset0:68 offset1:70
	s_and_b64 s[0:1], s[34:35], exec
	s_cselect_b32 s0, s4, s5
	s_lshl_b32 s0, s0, 6
	s_add_i32 s38, s0, s44
	s_ashr_i32 s39, s38, 31
	s_waitcnt lgkmcnt(0)
	v_mfma_f32_32x32x16_bf16 v[128:143], v[112:115], v[116:119], 0
	ds_read2_b64 v[116:119], v196 offset0:72 offset1:74
	v_mfma_f32_32x32x16_bf16 v[96:111], v[242:245], v[238:241], v[96:111]
	ds_read2_b64 v[238:241], v15 offset0:12 offset1:14
	v_cvt_pk_bf16_f32 v242, v64, v65
	v_cvt_pk_bf16_f32 v243, v66, v67
	v_cvt_pk_bf16_f32 v244, v68, v69
	v_cvt_pk_bf16_f32 v245, v70, v71
	s_waitcnt lgkmcnt(0)
	v_mfma_f32_32x32x16_bf16 v[112:127], v[112:115], v[116:119], 0
	v_mfma_f32_32x32x16_bf16 v[128:143], v[246:249], v[238:241], v[128:143]
	ds_read2_b64 v[238:241], v196 offset0:76 offset1:78
	s_waitcnt lgkmcnt(0)
	v_mfma_f32_32x32x16_bf16 v[112:127], v[246:249], v[238:241], v[112:127]
	v_cvt_pk_bf16_f32 v238, v48, v49
	v_cvt_pk_bf16_f32 v239, v50, v51
	v_cvt_pk_bf16_f32 v240, v52, v53
	v_cvt_pk_bf16_f32 v241, v54, v55
	ds_read2_b64 v[246:249], v15 offset0:16 offset1:18
	s_waitcnt lgkmcnt(0)
	v_mfma_f32_32x32x16_bf16 v[80:95], v[238:241], v[246:249], v[80:95]
	ds_read2_b64 v[246:249], v196 offset0:80 offset1:82
	s_waitcnt lgkmcnt(0)
	v_mfma_f32_32x32x16_bf16 v[96:111], v[238:241], v[246:249], v[96:111]
	ds_read2_b64 v[238:241], v15 offset0:24 offset1:26
	ds_read2_b64 v[246:249], v15 offset0:20 offset1:22
	s_waitcnt lgkmcnt(0)
	v_mfma_f32_32x32x16_bf16 v[128:143], v[242:245], v[238:241], v[128:143]
	ds_read2_b64 v[238:241], v196 offset0:88 offset1:90
	s_waitcnt lgkmcnt(0)
	v_mfma_f32_32x32x16_bf16 v[112:127], v[242:245], v[238:241], v[112:127]
	v_cvt_pk_bf16_f32 v238, v56, v57
	v_cvt_pk_bf16_f32 v239, v58, v59
	v_cvt_pk_bf16_f32 v240, v60, v61
	v_cvt_pk_bf16_f32 v241, v62, v63
	v_cvt_pk_bf16_f32 v242, v72, v73
	v_cvt_pk_bf16_f32 v243, v74, v75
	v_cvt_pk_bf16_f32 v244, v76, v77
	v_mfma_f32_32x32x16_bf16 v[80:95], v[238:241], v[246:249], v[80:95]
	ds_read2_b64 v[246:249], v196 offset0:84 offset1:86
	v_cvt_pk_bf16_f32 v245, v78, v79
	s_waitcnt lgkmcnt(0)
	v_mfma_f32_32x32x16_bf16 v[96:111], v[238:241], v[246:249], v[96:111]
	ds_read2_b64 v[238:241], v15 offset0:28 offset1:30
	v_ashrrev_i32_e32 v15, 31, v14
	s_waitcnt lgkmcnt(0)
	v_mfma_f32_32x32x16_bf16 v[128:143], v[242:245], v[238:241], v[128:143]
	ds_read2_b64 v[238:241], v196 offset0:92 offset1:94
	v_lshl_add_u32 v196, v215, 2, s71
	v_ashrrev_i32_e32 v197, 31, v196
	v_lshlrev_b64 v[196:197], 15, v[196:197]
	v_lshl_add_u64 v[196:197], s[68:69], 0, v[196:197]
	v_lshl_add_u64 v[196:197], s[38:39], 1, v[196:197]
	v_lshl_add_u64 v[196:197], v[14:15], 1, v[196:197]
	s_waitcnt lgkmcnt(0)
	v_mfma_f32_32x32x16_bf16 v[112:127], v[242:245], v[238:241], v[112:127]
	s_nop 2
	v_add_f32_e32 v15, v80, v128
	v_bfe_u32 v80, v15, 16, 1
	v_add3_u32 v15, v15, v80, s55
	global_store_short_d16_hi v[196:197], v15, off
	s_nop 4
	v_add_f32_e32 v15, v96, v112
	v_bfe_u32 v80, v15, 16, 1
	v_add3_u32 v15, v15, v80, s55
	global_store_short_d16_hi v[196:197], v15, off offset:64
	v_add_f32_e32 v15, v81, v129
	v_bfe_u32 v80, v15, 16, 1
	v_add3_u32 v15, v15, v80, s55
	v_add_co_u32_e32 v80, vcc, s47, v196
	s_nop 1
	v_addc_co_u32_e32 v81, vcc, 0, v197, vcc
	global_store_short_d16_hi v[80:81], v15, off
	v_add_f32_e32 v15, v97, v113
	v_bfe_u32 v96, v15, 16, 1
	v_add3_u32 v15, v15, v96, s55
	global_store_short_d16_hi v[80:81], v15, off offset:64
	v_add_f32_e32 v15, v82, v130
	v_bfe_u32 v80, v15, 16, 1
	v_add3_u32 v15, v15, v80, s55
	v_add_co_u32_e32 v80, vcc, s33, v196
	s_nop 1
	v_addc_co_u32_e32 v81, vcc, 0, v197, vcc
	global_store_short_d16_hi v[80:81], v15, off
	v_add_f32_e32 v15, v98, v114
	v_bfe_u32 v82, v15, 16, 1
	v_add3_u32 v15, v15, v82, s55
	global_store_short_d16_hi v[80:81], v15, off offset:64
	v_add_f32_e32 v15, v83, v131
	v_bfe_u32 v80, v15, 16, 1
	v_add3_u32 v15, v15, v80, s55
	v_add_co_u32_e32 v80, vcc, s46, v196
	s_nop 1
	v_addc_co_u32_e32 v81, vcc, 0, v197, vcc
	global_store_short_d16_hi v[80:81], v15, off
	v_add_f32_e32 v15, v99, v115
	v_bfe_u32 v82, v15, 16, 1
	v_add3_u32 v15, v15, v82, s55
	global_store_short_d16_hi v[80:81], v15, off offset:64
	v_add_f32_e32 v15, v84, v132
	v_bfe_u32 v80, v15, 16, 1
	v_add3_u32 v15, v15, v80, s55
	v_add_co_u32_e32 v80, vcc, s82, v196
	s_nop 1
	v_addc_co_u32_e32 v81, vcc, 0, v197, vcc
	global_store_short_d16_hi v[80:81], v15, off
	v_add_f32_e32 v15, v100, v116
	v_bfe_u32 v82, v15, 16, 1
	v_add3_u32 v15, v15, v82, s55
	global_store_short_d16_hi v[80:81], v15, off offset:64
	v_add_f32_e32 v15, v85, v133
	v_bfe_u32 v80, v15, 16, 1
	v_add3_u32 v15, v15, v80, s55
	v_add_co_u32_e32 v80, vcc, s83, v196
	s_nop 1
	v_addc_co_u32_e32 v81, vcc, 0, v197, vcc
	global_store_short_d16_hi v[80:81], v15, off
	v_add_f32_e32 v15, v101, v117
	v_bfe_u32 v82, v15, 16, 1
	v_add3_u32 v15, v15, v82, s55
	global_store_short_d16_hi v[80:81], v15, off offset:64
	v_add_f32_e32 v15, v86, v134
	v_bfe_u32 v80, v15, 16, 1
	v_add3_u32 v15, v15, v80, s55
	v_add_co_u32_e32 v80, vcc, s54, v196
	s_nop 1
	v_addc_co_u32_e32 v81, vcc, 0, v197, vcc
	global_store_short_d16_hi v[80:81], v15, off
	v_add_f32_e32 v15, v102, v118
	v_bfe_u32 v82, v15, 16, 1
	v_add3_u32 v15, v15, v82, s55
	global_store_short_d16_hi v[80:81], v15, off offset:64
	v_add_f32_e32 v15, v87, v135
	v_bfe_u32 v80, v15, 16, 1
	v_add3_u32 v15, v15, v80, s55
	v_add_co_u32_e32 v80, vcc, s88, v196
	s_nop 1
	v_addc_co_u32_e32 v81, vcc, 0, v197, vcc
	global_store_short_d16_hi v[80:81], v15, off
	v_add_f32_e32 v15, v103, v119
	v_bfe_u32 v82, v15, 16, 1
	v_add3_u32 v15, v15, v82, s55
	global_store_short_d16_hi v[80:81], v15, off offset:64
	v_add_f32_e32 v15, v88, v136
	v_bfe_u32 v80, v15, 16, 1
	v_add3_u32 v15, v15, v80, s55
	v_add_co_u32_e32 v80, vcc, s48, v196
	s_nop 1
	v_addc_co_u32_e32 v81, vcc, 0, v197, vcc
	global_store_short_d16_hi v[80:81], v15, off
	v_add_f32_e32 v15, v104, v120
	v_bfe_u32 v82, v15, 16, 1
	v_add3_u32 v15, v15, v82, s55
	global_store_short_d16_hi v[80:81], v15, off offset:64
	v_add_f32_e32 v15, v89, v137
	v_bfe_u32 v80, v15, 16, 1
	v_add3_u32 v15, v15, v80, s55
	v_add_co_u32_e32 v80, vcc, s51, v196
	s_nop 1
	v_addc_co_u32_e32 v81, vcc, 0, v197, vcc
	global_store_short_d16_hi v[80:81], v15, off
	v_add_f32_e32 v15, v105, v121
	v_bfe_u32 v82, v15, 16, 1
	v_add3_u32 v15, v15, v82, s55
	global_store_short_d16_hi v[80:81], v15, off offset:64
	v_add_f32_e32 v15, v90, v138
	v_bfe_u32 v80, v15, 16, 1
	v_add3_u32 v15, v15, v80, s55
	v_add_co_u32_e32 v80, vcc, s52, v196
	s_nop 1
	v_addc_co_u32_e32 v81, vcc, 0, v197, vcc
	global_store_short_d16_hi v[80:81], v15, off
	v_add_f32_e32 v15, v106, v122
	v_bfe_u32 v82, v15, 16, 1
	v_add3_u32 v15, v15, v82, s55
	global_store_short_d16_hi v[80:81], v15, off offset:64
	v_add_f32_e32 v15, v91, v139
	v_bfe_u32 v80, v15, 16, 1
	v_add3_u32 v15, v15, v80, s55
	v_add_co_u32_e32 v80, vcc, s90, v196
	s_nop 1
	v_addc_co_u32_e32 v81, vcc, 0, v197, vcc
	global_store_short_d16_hi v[80:81], v15, off
	v_add_f32_e32 v15, v107, v123
	v_bfe_u32 v82, v15, 16, 1
	v_add3_u32 v15, v15, v82, s55
	global_store_short_d16_hi v[80:81], v15, off offset:64
	v_add_f32_e32 v15, v92, v140
	v_bfe_u32 v80, v15, 16, 1
	v_add3_u32 v15, v15, v80, s55
	v_add_co_u32_e32 v80, vcc, s91, v196
	s_nop 1
	v_addc_co_u32_e32 v81, vcc, 0, v197, vcc
	global_store_short_d16_hi v[80:81], v15, off
	v_add_f32_e32 v15, v108, v124
	v_bfe_u32 v82, v15, 16, 1
	v_add3_u32 v15, v15, v82, s55
	global_store_short_d16_hi v[80:81], v15, off offset:64
	v_add_f32_e32 v15, v93, v141
	v_bfe_u32 v80, v15, 16, 1
	v_add3_u32 v15, v15, v80, s55
	v_add_co_u32_e32 v80, vcc, s84, v196
	s_nop 1
	v_addc_co_u32_e32 v81, vcc, 0, v197, vcc
	global_store_short_d16_hi v[80:81], v15, off
	v_add_f32_e32 v15, v109, v125
	v_bfe_u32 v82, v15, 16, 1
	v_add3_u32 v15, v15, v82, s55
	global_store_short_d16_hi v[80:81], v15, off offset:64
	v_add_f32_e32 v15, v94, v142
	v_bfe_u32 v80, v15, 16, 1
	v_add3_u32 v15, v15, v80, s55
	v_add_co_u32_e32 v80, vcc, s65, v196
	s_nop 1
	v_addc_co_u32_e32 v81, vcc, 0, v197, vcc
	global_store_short_d16_hi v[80:81], v15, off
	v_add_f32_e32 v15, v110, v126
	v_bfe_u32 v82, v15, 16, 1
	v_add3_u32 v15, v15, v82, s55
	global_store_short_d16_hi v[80:81], v15, off offset:64
	v_add_f32_e32 v15, v95, v143
	v_bfe_u32 v80, v15, 16, 1
	v_add3_u32 v15, v15, v80, s55
	v_add_co_u32_e32 v80, vcc, s66, v196
	s_nop 1
	v_addc_co_u32_e32 v81, vcc, 0, v197, vcc
	global_store_short_d16_hi v[80:81], v15, off
	v_add_f32_e32 v15, v111, v127
	v_bfe_u32 v82, v15, 16, 1
	v_add3_u32 v15, v15, v82, s55
	global_store_short_d16_hi v[80:81], v15, off offset:64
	v_lshl_add_u32 v15, v215, 4, 0
	v_add_u32_e32 v15, 0x17400, v15
	ds_read_b128 v[80:83], v15
	ds_read_b128 v[84:87], v15 offset:32
	ds_read_b128 v[88:91], v15 offset:64
	ds_read_b128 v[92:95], v15 offset:96
	v_mov_b32_e32 v215, v209
	s_waitcnt lgkmcnt(0)
	v_pk_mul_f32 v[18:19], v[18:19], v[82:83]
	v_pk_mul_f32 v[22:23], v[22:23], v[86:87]
	v_pk_mul_f32 v[26:27], v[26:27], v[90:91]
	v_pk_mul_f32 v[30:31], v[30:31], v[94:95]
	v_pk_mul_f32 v[28:29], v[28:29], v[92:93]
	v_pk_mul_f32 v[24:25], v[24:25], v[88:89]
	v_pk_mul_f32 v[20:21], v[20:21], v[84:85]
	v_pk_mul_f32 v[16:17], v[16:17], v[80:81]
	ds_read_b128 v[80:83], v15 offset:128
	ds_read_b128 v[84:87], v15 offset:160
	ds_read_b128 v[88:91], v15 offset:192
	ds_read_b128 v[92:95], v15 offset:224
	s_waitcnt lgkmcnt(0)
	v_pk_mul_f32 v[34:35], v[34:35], v[82:83]
	v_pk_mul_f32 v[38:39], v[38:39], v[86:87]
	v_pk_mul_f32 v[42:43], v[42:43], v[90:91]
	v_pk_mul_f32 v[46:47], v[46:47], v[94:95]
	v_pk_mul_f32 v[44:45], v[44:45], v[92:93]
	v_pk_mul_f32 v[40:41], v[40:41], v[88:89]
	v_pk_mul_f32 v[36:37], v[36:37], v[84:85]
	v_pk_mul_f32 v[32:33], v[32:33], v[80:81]
	ds_read_b128 v[80:83], v15 offset:256
	ds_read_b128 v[84:87], v15 offset:288
	ds_read_b128 v[88:91], v15 offset:320
	ds_read_b128 v[92:95], v15 offset:352
	s_waitcnt lgkmcnt(0)
	v_pk_mul_f32 v[50:51], v[50:51], v[82:83]
	v_pk_mul_f32 v[54:55], v[54:55], v[86:87]
	v_pk_mul_f32 v[58:59], v[58:59], v[90:91]
	v_pk_mul_f32 v[62:63], v[62:63], v[94:95]
	v_pk_mul_f32 v[60:61], v[60:61], v[92:93]
	v_pk_mul_f32 v[56:57], v[56:57], v[88:89]
	v_pk_mul_f32 v[52:53], v[52:53], v[84:85]
	v_pk_mul_f32 v[48:49], v[48:49], v[80:81]
	ds_read_b128 v[80:83], v15 offset:384
	ds_read_b128 v[84:87], v15 offset:416
	ds_read_b128 v[88:91], v15 offset:448
	ds_read_b128 v[92:95], v15 offset:480
	v_add_u32_e32 v15, s76, v14
	s_waitcnt lgkmcnt(0)
	v_pk_mul_f32 v[64:65], v[64:65], v[80:81]
	v_mad_u64_u32 v[80:81], s[0:1], v15, s53, v[0:1]
	v_mul_lo_u32 v14, v14, s63
	v_lshl_add_u32 v15, v80, 1, 0
	v_add_u32_e32 v80, v0, v14
	v_lshl_add_u32 v80, v80, 1, 0
	v_add_u32_e32 v80, 0x8800, v80
	v_pk_mul_f32 v[74:75], v[74:75], v[90:91]
	v_pk_mul_f32 v[70:71], v[70:71], v[86:87]
	v_pk_mul_f32 v[66:67], v[66:67], v[82:83]
	v_pk_mul_f32 v[72:73], v[72:73], v[88:89]
	v_pk_mul_f32 v[68:69], v[68:69], v[84:85]
	ds_read2_b64 v[80:83], v80 offset1:1
	ds_read_b128 v[84:87], v15 offset:52224
	ds_read_b128 v[88:91], v15 offset:52256
	v_pk_mul_f32 v[76:77], v[76:77], v[92:93]
	v_add_u32_e32 v92, 0x880, v14
	s_waitcnt lgkmcnt(0)
	v_mfma_f32_32x32x16_bf16 v[16:31], v[80:83], v[84:87], v[16:31]
	v_add_u32_e32 v80, v92, v0
	v_lshl_add_u32 v80, v80, 1, 0
	v_add_u32_e32 v80, 0x8800, v80
	ds_read2_b64 v[80:83], v80 offset1:1
	v_add_u32_e32 v93, 0x1100, v14
	v_pk_mul_f32 v[78:79], v[78:79], v[94:95]
	v_add_u32_e32 v94, 0x1980, v14
	s_waitcnt lgkmcnt(0)
	v_mfma_f32_32x32x16_bf16 v[32:47], v[80:83], v[84:87], v[32:47]
	v_add_u32_e32 v80, v93, v0
	v_lshl_add_u32 v80, v80, 1, 0
	v_add_u32_e32 v80, 0x8800, v80
	ds_read2_b64 v[80:83], v80 offset1:1
	s_waitcnt lgkmcnt(0)
	v_mfma_f32_32x32x16_bf16 v[48:63], v[80:83], v[84:87], v[48:63]
	v_add_u32_e32 v80, v94, v0
	v_lshl_add_u32 v80, v80, 1, 0
	v_add_u32_e32 v80, 0x8800, v80
	ds_read2_b64 v[80:83], v80 offset1:1
	s_waitcnt lgkmcnt(0)
	v_mfma_f32_32x32x16_bf16 v[64:79], v[80:83], v[84:87], v[64:79]
	v_add_u32_e32 v84, 16, v0
	v_add_u32_e32 v80, v84, v14
	v_lshl_add_u32 v80, v80, 1, 0
	v_add_u32_e32 v80, 0x8800, v80
	ds_read2_b64 v[80:83], v80 offset1:1
	s_waitcnt lgkmcnt(0)
	v_mfma_f32_32x32x16_bf16 v[16:31], v[80:83], v[88:91], v[16:31]
	v_add_u32_e32 v80, v84, v92
	v_lshl_add_u32 v80, v80, 1, 0
	v_add_u32_e32 v80, 0x8800, v80
	ds_read2_b64 v[80:83], v80 offset1:1
	s_waitcnt lgkmcnt(0)
	v_mfma_f32_32x32x16_bf16 v[32:47], v[80:83], v[88:91], v[32:47]
	v_add_u32_e32 v80, v84, v93
	v_lshl_add_u32 v80, v80, 1, 0
	v_add_u32_e32 v80, 0x8800, v80
	ds_read2_b64 v[80:83], v80 offset1:1
	s_waitcnt lgkmcnt(0)
	v_mfma_f32_32x32x16_bf16 v[48:63], v[80:83], v[88:91], v[48:63]
	v_add_u32_e32 v80, v84, v94
	v_lshl_add_u32 v80, v80, 1, 0
	v_add_u32_e32 v80, 0x8800, v80
	ds_read2_b64 v[80:83], v80 offset1:1
	s_waitcnt lgkmcnt(0)
	v_mfma_f32_32x32x16_bf16 v[64:79], v[80:83], v[88:91], v[64:79]
	v_add_u32_e32 v88, 32, v0
	v_add_u32_e32 v84, v88, v14
	v_lshl_add_u32 v84, v84, 1, 0
	v_add_u32_e32 v84, 0x8800, v84
	ds_read_b128 v[80:83], v15 offset:52288
	ds_read2_b64 v[84:87], v84 offset1:1
	v_add_u32_e32 v0, 48, v0
	s_waitcnt lgkmcnt(0)
	v_mfma_f32_32x32x16_bf16 v[16:31], v[84:87], v[80:83], v[16:31]
	v_add_u32_e32 v84, v88, v92
	v_lshl_add_u32 v84, v84, 1, 0
	v_add_u32_e32 v84, 0x8800, v84
	ds_read2_b64 v[84:87], v84 offset1:1
	v_add_u32_e32 v14, v0, v14
	v_lshl_add_u32 v14, v14, 1, 0
	v_add_u32_e32 v14, 0x8800, v14
	s_waitcnt lgkmcnt(0)
	v_mfma_f32_32x32x16_bf16 v[32:47], v[84:87], v[80:83], v[32:47]
	v_add_u32_e32 v84, v88, v93
	v_lshl_add_u32 v84, v84, 1, 0
	v_add_u32_e32 v84, 0x8800, v84
	ds_read2_b64 v[84:87], v84 offset1:1
	s_waitcnt lgkmcnt(0)
	v_mfma_f32_32x32x16_bf16 v[48:63], v[84:87], v[80:83], v[48:63]
	v_add_u32_e32 v84, v88, v94
	v_lshl_add_u32 v84, v84, 1, 0
	v_add_u32_e32 v84, 0x8800, v84
	ds_read2_b64 v[84:87], v84 offset1:1
	s_waitcnt lgkmcnt(0)
	v_mfma_f32_32x32x16_bf16 v[64:79], v[84:87], v[80:83], v[64:79]
	ds_read_b128 v[80:83], v15 offset:52320
	ds_read2_b64 v[84:87], v14 offset1:1
	v_add_u32_e32 v14, v0, v92
	v_lshl_add_u32 v14, v14, 1, 0
	v_add_u32_e32 v14, 0x8800, v14
	s_waitcnt lgkmcnt(0)
	v_mfma_f32_32x32x16_bf16 v[16:31], v[84:87], v[80:83], v[16:31]
	ds_read2_b64 v[84:87], v14 offset1:1
	v_add_u32_e32 v14, v0, v93
	v_lshl_add_u32 v14, v14, 1, 0
	v_add_u32_e32 v14, 0x8800, v14
	v_add_u32_e32 v0, v0, v94
	v_lshl_add_u32 v0, v0, 1, 0
	v_add_u32_e32 v0, 0x8800, v0
	s_waitcnt lgkmcnt(0)
	v_mfma_f32_32x32x16_bf16 v[32:47], v[84:87], v[80:83], v[32:47]
	ds_read2_b64 v[84:87], v14 offset1:1
	v_mov_b32_e32 v14, v208
	s_waitcnt lgkmcnt(0)
	v_mfma_f32_32x32x16_bf16 v[48:63], v[84:87], v[80:83], v[48:63]
	ds_read2_b64 v[84:87], v0 offset1:1
	v_mov_b32_e32 v0, v236
	s_waitcnt lgkmcnt(0)
	v_ashrrev_i32_e32 v15, 4, v0
	s_barrier
	s_waitcnt vmcnt(63)
	v_mfma_f32_32x32x16_bf16 v[64:79], v[84:87], v[80:83], v[64:79]
	v_lshlrev_b32_e32 v82, 3, v0
	v_and_b32_e32 v80, 0x78, v82
	v_mad_u64_u32 v[80:81], s[0:1], v15, s31, v[80:81]
	v_lshl_add_u32 v15, v80, 1, 0
	ds_write_b128 v15, v[164:167]
	ds_write_b128 v15, v[168:171] offset:8704
	v_ashrrev_i32_e32 v15, 3, v0
	v_and_b32_e32 v80, 56, v82
	v_mad_u64_u32 v[82:83], s[0:1], v15, s63, v[80:81]
	v_lshl_add_u32 v81, v82, 1, 0
	v_lshl_add_u32 v15, v15, 2, v82
	v_add_u32_e32 v83, 0x8800, v81
	v_lshl_add_u32 v15, v15, 1, 0
	v_add_u32_e32 v81, 0xaa00, v81
	ds_write2_b64 v83, v[172:173], v[174:175] offset1:1
	ds_write2_b64 v81, v[176:177], v[178:179] offset1:1
	ds_write_b128 v15, v[180:183] offset:52224
	v_add_u32_e32 v15, 0x200, v0
	v_lshrrev_b32_e32 v15, 3, v15
	v_mad_u64_u32 v[82:83], s[0:1], v15, s53, v[80:81]
	v_lshl_add_u32 v15, v82, 1, 0
	ds_write_b128 v15, v[184:187] offset:52224
	v_add_u32_e32 v15, 0x400, v0
	v_lshrrev_b32_e32 v15, 3, v15
	v_mad_u64_u32 v[82:83], s[0:1], v15, s53, v[80:81]
	v_lshl_add_u32 v15, v82, 1, 0
	ds_write_b128 v15, v[188:191] offset:52224
	v_add_u32_e32 v15, 0x600, v0
	v_lshrrev_b32_e32 v15, 3, v15
	v_mad_u64_u32 v[80:81], s[0:1], v15, s53, v[80:81]
	v_lshl_add_u32 v15, v80, 1, 0
	v_cmp_gt_i32_e32 vcc, s60, v0
	ds_write_b128 v15, v[192:195] offset:52224
	s_and_saveexec_b64 s[38:39], vcc
	v_lshl_add_u32 v0, v0, 2, 0
	v_add_u32_e32 v0, 0x17400, v0
	ds_write_b32 v0, v213
	s_or_b64 exec, exec, s[38:39]
	s_cmp_ge_u32 s79, s43
	s_waitcnt lgkmcnt(0)
	s_barrier
	s_cbranch_scc1 .LBB0_493
	s_and_b64 s[0:1], s[34:35], exec
	s_cselect_b32 s0, s79, s78
	s_lshl_b32 s0, s0, 6
	s_add_i32 s0, s0, s44
	s_ashr_i32 s1, s0, 4
	s_or_b32 s1, s1, s11
	s_lshl_b32 s1, s1, 1
	s_or_b32 s38, s1, s42
	s_ashr_i32 s39, s38, 31
	s_lshl_b64 s[4:5], s[38:39], 14
	s_add_u32 s6, s92, s4
	s_addc_u32 s7, s93, s5
	s_add_u32 s4, s73, s4
	v_mov_b32_e32 v80, v236
	s_addc_u32 s5, s74, s5
	s_ashr_i32 s1, s0, 31
	v_lshlrev_b32_e32 v0, 3, v80
	v_lshlrev_b64 v[82:83], 1, v[0:1]
	v_add_u32_e32 v86, 0x1000, v0
	v_mov_b32_e32 v87, v1
	s_lshl_b64 s[0:1], s[0:1], 1
	v_lshl_add_u64 v[84:85], s[6:7], 0, v[82:83]
	v_lshlrev_b64 v[86:87], 1, v[86:87]
	s_add_u32 s0, s45, s0
	v_lshlrev_b32_e32 v15, 11, v80
	v_and_b32_e32 v0, 56, v0
	v_lshl_add_u64 v[88:89], s[6:7], 0, v[86:87]
	global_load_dwordx4 v[164:167], v[84:85], off
	global_load_dwordx4 v[168:171], v[88:89], off
	v_lshl_add_u64 v[82:83], s[4:5], 0, v[82:83]
	v_lshl_add_u64 v[84:85], s[4:5], 0, v[86:87]
	s_addc_u32 s1, s70, s1
	v_and_or_b32 v0, v15, s62, v0
	global_load_dwordx4 v[172:175], v[82:83], off
	global_load_dwordx4 v[176:179], v[84:85], off
	v_lshl_add_u64 v[82:83], v[0:1], 1, s[0:1]
	v_add_u32_e32 v84, 0x100000, v0
	v_mov_b32_e32 v85, v1
	v_lshl_add_u64 v[84:85], v[84:85], 1, s[0:1]
	global_load_dwordx4 v[180:183], v[82:83], off
	global_load_dwordx4 v[184:187], v[84:85], off
	v_add_u32_e32 v82, 0x200000, v0
	v_mov_b32_e32 v83, v1
	v_lshl_add_u64 v[82:83], v[82:83], 1, s[0:1]
	v_add_u32_e32 v0, 0x300000, v0
	v_lshl_add_u64 v[84:85], v[0:1], 1, s[0:1]
	global_load_dwordx4 v[188:191], v[82:83], off
	global_load_dwordx4 v[192:195], v[84:85], off
	v_cmp_gt_i32_e32 vcc, s60, v80
	s_and_saveexec_b64 s[40:41], vcc
	s_cbranch_execz .LBB0_492
	s_lshl_b64 s[0:1], s[38:39], 9
	s_add_u32 s0, s75, s0
	s_addc_u32 s1, s86, s1
	v_mov_b32_e32 v81, v1
	v_lshl_add_u64 v[80:81], v[80:81], 2, s[0:1]
	global_load_dword v213, v[80:81], off
	s_branch .LBB0_492
